# tile-1 K/V prefetch issued in the attention unit prologue; nt policy on MLP-up hidden-activation stores
# baseline (speedup 1.0000x reference)
.LBB0_1012:
	s_ashr_i32 s39, s0, 7
	s_lshl_b32 s4, s0, 9
	s_bfe_u32 s1, s0, 0x40003
	s_and_b32 s40, s4, 0xe00
	s_lshl_b32 s4, s39, 4
	s_or_b32 s4, s4, s1
	s_add_i32 s40, s40, s38
	s_ashr_i32 s5, s4, 31
	s_lshr_b32 s6, s0, 3
	s_lshl_b64 s[4:5], s[4:5], 12
	s_ashr_i32 s7, s40, 31
	s_add_u32 s4, s4, s40
	s_addc_u32 s5, s5, s7
	v_mov_b32_e32 v1, s5
	v_or_b32_e32 v0, s4, v202
	s_bfe_u32 s4, s6, 0x20002
	s_lshl_b32 s5, s39, 2
	s_or_b32 s4, s4, s5
	v_lshlrev_b64 v[0:1], 7, v[0:1]
	s_ashr_i32 s5, s4, 31
	v_lshl_add_u64 v[2:3], v[204:205], 0, v[0:1]
	v_or_b32_e32 v0, 0x1000, v0
	s_lshl_b64 s[4:5], s[4:5], 19
	v_lshl_add_u64 v[0:1], v[204:205], 0, v[0:1]
	v_lshl_add_u64 v[212:213], v[208:209], 0, s[4:5]
	global_load_dwordx4 v[130:133], v[2:3], off
	global_load_dwordx4 v[134:137], v[2:3], off offset:32
	global_load_dwordx4 v[138:141], v[2:3], off offset:64
	global_load_dwordx4 v[142:145], v[2:3], off offset:96
	global_load_dwordx4 v[146:149], v[0:1], off
	global_load_dwordx4 v[150:153], v[0:1], off offset:32
	global_load_dwordx4 v[154:157], v[0:1], off offset:64
	global_load_dwordx4 v[158:161], v[0:1], off offset:96
	v_lshl_add_u64 v[214:215], v[210:211], 0, s[4:5]
	global_load_dwordx4 v[0:3], v[212:213], off
	global_load_dwordx4 v[4:7], v[214:215], off
	s_mov_b64 s[6:7], 0x2000
	v_lshl_add_u64 v[182:183], v[212:213], 0, s[6:7]
	global_load_dwordx4 v[182:185], v[182:183], off
	global_load_dwordx4 v[178:181], v[214:215], off offset:128
	v_mov_b32_e32 v82, 0xf149f2ca
	s_mov_b32 s4, 0
	s_movk_i32 s42, 0x6c00
	s_movk_i32 s41, 0x4800
	s_mov_b32 s5, 0x9000
	v_mov_b32_e32 v162, 0
	v_mov_b32_e32 v163, 0
	v_mov_b32_e32 v164, 0
	v_mov_b32_e32 v165, 0
	v_mov_b32_e32 v174, 0
	v_mov_b32_e32 v175, 0
	v_mov_b32_e32 v176, 0
	v_mov_b32_e32 v177, 0
	v_mov_b32_e32 v166, 0
	v_mov_b32_e32 v167, 0
	v_mov_b32_e32 v168, 0
	v_mov_b32_e32 v169, 0
	v_mov_b32_e32 v170, 0
	v_mov_b32_e32 v171, 0
	v_mov_b32_e32 v172, 0
	v_mov_b32_e32 v173, 0
	v_mov_b32_e32 v83, v82
	v_mov_b32_e32 v84, v82
	v_mov_b32_e32 v85, v82
	v_mov_b32_e32 v86, v82
	v_mov_b32_e32 v87, v82
	v_mov_b32_e32 v88, v82
	v_mov_b32_e32 v89, v82
	v_mov_b32_e32 v90, v82
	v_mov_b32_e32 v91, v82
	v_mov_b32_e32 v92, v82
	v_mov_b32_e32 v93, v82
	v_mov_b32_e32 v94, v82
	v_mov_b32_e32 v95, v82
	v_mov_b32_e32 v96, v82
	v_mov_b32_e32 v97, v82
	v_mov_b32_e32 v66, v82
	v_mov_b32_e32 v67, v82
	v_mov_b32_e32 v68, v82
	v_mov_b32_e32 v69, v82
	v_mov_b32_e32 v70, v82
	v_mov_b32_e32 v71, v82
	v_mov_b32_e32 v72, v82
	v_mov_b32_e32 v73, v82
	v_mov_b32_e32 v74, v82
	v_mov_b32_e32 v75, v82
	v_mov_b32_e32 v76, v82
	v_mov_b32_e32 v77, v82
	v_mov_b32_e32 v78, v82
	v_mov_b32_e32 v79, v82
	v_mov_b32_e32 v80, v82
	v_mov_b32_e32 v81, v82
	s_waitcnt vmcnt(3)
	ds_write_b128 v203, v[0:3]
	s_waitcnt vmcnt(2)
	ds_write_b128 v203, v[4:7] offset:18432
	v_mov_b32_e32 v0, 0
	v_mov_b32_e32 v1, v0
	v_mov_b32_e32 v2, v0
	v_mov_b32_e32 v3, v0
	v_mov_b32_e32 v4, v0
	v_mov_b32_e32 v5, v0
	v_mov_b32_e32 v6, v0
	v_mov_b32_e32 v7, v0
	v_mov_b32_e32 v8, v0
	v_mov_b32_e32 v9, v0
	v_mov_b32_e32 v10, v0
	v_mov_b32_e32 v11, v0
	v_mov_b32_e32 v12, v0
	v_mov_b32_e32 v13, v0
	v_mov_b32_e32 v14, v0
	v_mov_b32_e32 v15, v0
	v_mov_b32_e32 v16, v0
	v_mov_b32_e32 v17, v0
	v_mov_b32_e32 v18, v0
	v_mov_b32_e32 v19, v0
	v_mov_b32_e32 v20, v0
	v_mov_b32_e32 v21, v0
	v_mov_b32_e32 v22, v0
	v_mov_b32_e32 v23, v0
	v_mov_b32_e32 v24, v0
	v_mov_b32_e32 v25, v0
	v_mov_b32_e32 v26, v0
	v_mov_b32_e32 v27, v0
	v_mov_b32_e32 v28, v0
	v_mov_b32_e32 v29, v0
	v_mov_b32_e32 v30, v0
	v_mov_b32_e32 v31, v0
	v_mov_b32_e32 v34, v0
	v_mov_b32_e32 v35, v0
	v_mov_b32_e32 v36, v0
	v_mov_b32_e32 v37, v0
	v_mov_b32_e32 v38, v0
	v_mov_b32_e32 v39, v0
	v_mov_b32_e32 v40, v0
	v_mov_b32_e32 v41, v0
	v_mov_b32_e32 v42, v0
	v_mov_b32_e32 v43, v0
	v_mov_b32_e32 v44, v0
	v_mov_b32_e32 v45, v0
	v_mov_b32_e32 v46, v0
	v_mov_b32_e32 v47, v0
	v_mov_b32_e32 v48, v0
	v_mov_b32_e32 v49, v0
	v_mov_b32_e32 v50, v0
	v_mov_b32_e32 v51, v0
	v_mov_b32_e32 v52, v0
	v_mov_b32_e32 v53, v0
	v_mov_b32_e32 v54, v0
	v_mov_b32_e32 v55, v0
	v_mov_b32_e32 v56, v0
	v_mov_b32_e32 v57, v0
	v_mov_b32_e32 v58, v0
	v_mov_b32_e32 v59, v0
	v_mov_b32_e32 v60, v0
	v_mov_b32_e32 v61, v0
	v_mov_b32_e32 v62, v0
	v_mov_b32_e32 v63, v0
	v_mov_b32_e32 v64, v0
	v_mov_b32_e32 v65, v0
	v_mov_b32_e32 v216, v0
	v_mov_b32_e32 v217, v0
	s_waitcnt lgkmcnt(0)
	s_barrier
	v_mov_b32_e32 v234, v245
	v_add_u32_e32 v235, s5, v32
	ds_read_b128 v[226:229], v235
	ds_read_b128 v[230:233], v235 offset:4608
.LBB0_1013:
	s_waitcnt lgkmcnt(1)
	v_mfma_f32_32x32x16_bf16 v[50:65], v[226:229], v[170:173], v[50:65]
	s_add_i32 s44, s4, 1
	s_and_b32 s43, s44, 1
	s_mul_i32 s43, s43, 0x2400
	v_add_u32_e32 v199, s42, v203
	v_add_u32_e32 v198, s43, v203
	s_add_i32 s16, s4, 2
	s_min_u32 s16, s16, 63
	s_waitcnt vmcnt(0)
	ds_write_b128 v199, v[178:181]
	ds_write_b128 v198, v[182:185]
	s_lshl_b64 s[6:7], s[16:17], 13
	ds_read_b128 v[246:249], v235 offset:32
	v_lshl_add_u64 v[182:183], v[212:213], 0, s[6:7]
	s_lshl_b64 s[6:7], s[16:17], 7
	global_load_dwordx4 v[182:185], v[182:183], off
	v_lshl_add_u64 v[178:179], v[214:215], 0, s[6:7]
	global_load_dwordx4 v[178:181], v[178:179], off
	v_mfma_f32_32x32x16_bf16 v[16:31], v[226:229], v[174:177], v[16:31]
	v_exp_f32_e32 v82, v82
	v_exp_f32_e32 v83, v83
	v_exp_f32_e32 v84, v84
	v_exp_f32_e32 v85, v85
	v_exp_f32_e32 v86, v86
	s_waitcnt lgkmcnt(3)
	v_mfma_f32_32x32x16_bf16 v[34:49], v[230:233], v[170:173], v[34:49]
	v_exp_f32_e32 v87, v87
	v_exp_f32_e32 v88, v88
	v_exp_f32_e32 v89, v89
	v_cvt_pk_bf16_f32 v186, v82, v83
	v_add_f32_e32 v82, v82, v83
	ds_read_b128 v[226:229], v235 offset:4640
	v_mfma_f32_32x32x16_bf16 v[0:15], v[230:233], v[174:177], v[0:15]
	v_exp_f32_e32 v90, v90
	v_exp_f32_e32 v91, v91
	v_cvt_pk_bf16_f32 v187, v84, v85
	v_add_f32_e32 v84, v84, v85
	v_add_f32_e32 v217, v217, v82
	v_exp_f32_e32 v92, v92
	s_waitcnt lgkmcnt(1)
	v_mfma_f32_32x32x16_bf16 v[50:65], v[246:249], v[166:169], v[50:65]
	v_exp_f32_e32 v93, v93
	v_cvt_pk_bf16_f32 v188, v86, v87
	v_add_f32_e32 v86, v86, v87
	v_add_f32_e32 v217, v217, v84
	v_exp_f32_e32 v94, v94
	ds_read_b128 v[230:233], v234
	v_mfma_f32_32x32x16_bf16 v[16:31], v[246:249], v[162:165], v[16:31]
	v_exp_f32_e32 v95, v95
	v_cvt_pk_bf16_f32 v189, v88, v89
	v_add_f32_e32 v88, v88, v89
	v_add_f32_e32 v217, v217, v86
	v_exp_f32_e32 v96, v96
	s_waitcnt lgkmcnt(1)
	v_mfma_f32_32x32x16_bf16 v[34:49], v[226:229], v[166:169], v[34:49]
	v_exp_f32_e32 v97, v97
	v_cvt_pk_bf16_f32 v190, v90, v91
	v_add_f32_e32 v90, v90, v91
	v_add_f32_e32 v217, v217, v88
	v_exp_f32_e32 v66, v66
	v_exp_f32_e32 v67, v67
	ds_read_b128 v[246:249], v234 offset:32
	v_mfma_f32_32x32x16_bf16 v[0:15], v[226:229], v[162:165], v[0:15]
	v_cvt_pk_bf16_f32 v191, v92, v93
	v_add_f32_e32 v92, v92, v93
	v_add_f32_e32 v217, v217, v90
	v_exp_f32_e32 v68, v68
	v_exp_f32_e32 v69, v69
	s_waitcnt lgkmcnt(1)
	v_mfma_f32_32x32x16_bf16 v[114:129], v[230:233], v[130:133], 0
	v_cvt_pk_bf16_f32 v192, v94, v95
	v_add_f32_e32 v94, v94, v95
	v_add_f32_e32 v217, v217, v92
	v_exp_f32_e32 v70, v70
	v_exp_f32_e32 v71, v71
	ds_read_b128 v[226:229], v234 offset:64
	v_mfma_f32_32x32x16_bf16 v[98:113], v[230:233], v[146:149], 0
	v_cvt_pk_bf16_f32 v193, v96, v97
	v_add_f32_e32 v96, v96, v97
	v_add_f32_e32 v217, v217, v94
	v_exp_f32_e32 v72, v72
	v_exp_f32_e32 v73, v73
	v_cvt_pk_bf16_f32 v218, v66, v67
	s_waitcnt lgkmcnt(1)
	v_mfma_f32_32x32x16_bf16 v[114:129], v[246:249], v[134:137], v[114:129]
	v_add_f32_e32 v66, v66, v67
	v_add_f32_e32 v217, v217, v96
	v_exp_f32_e32 v74, v74
	v_exp_f32_e32 v75, v75
	v_cvt_pk_bf16_f32 v219, v68, v69
	ds_read_b128 v[230:233], v234 offset:96
	v_mfma_f32_32x32x16_bf16 v[98:113], v[246:249], v[150:153], v[98:113]
	v_add_f32_e32 v68, v68, v69
	v_add_f32_e32 v216, v216, v66
	v_exp_f32_e32 v76, v76
	v_exp_f32_e32 v77, v77
	v_cvt_pk_bf16_f32 v220, v70, v71
	s_waitcnt lgkmcnt(1)
	v_mfma_f32_32x32x16_bf16 v[114:129], v[226:229], v[138:141], v[114:129]
	v_add_f32_e32 v70, v70, v71
	v_add_f32_e32 v216, v216, v68
	v_exp_f32_e32 v78, v78
	v_exp_f32_e32 v79, v79
	v_cvt_pk_bf16_f32 v221, v72, v73
	v_add_f32_e32 v72, v72, v73
	v_mfma_f32_32x32x16_bf16 v[98:113], v[226:229], v[154:157], v[98:113]
	v_add_f32_e32 v216, v216, v70
	v_exp_f32_e32 v80, v80
	v_exp_f32_e32 v81, v81
	v_cvt_pk_bf16_f32 v222, v74, v75
	v_add_f32_e32 v74, v74, v75
	ds_read_b128 v[226:229], v235 offset:64
	s_waitcnt lgkmcnt(1)
	v_mfma_f32_32x32x16_bf16 v[114:129], v[230:233], v[142:145], v[114:129]
	v_add_f32_e32 v216, v216, v72
	v_cvt_pk_bf16_f32 v223, v76, v77
	v_add_f32_e32 v76, v76, v77
	v_add_f32_e32 v216, v216, v74
	v_cvt_pk_bf16_f32 v224, v78, v79
	v_mfma_f32_32x32x16_bf16 v[98:113], v[230:233], v[158:161], v[98:113]
	v_add_f32_e32 v78, v78, v79
	v_add_f32_e32 v216, v216, v76
	v_cvt_pk_bf16_f32 v225, v80, v81
	v_add_f32_e32 v80, v80, v81
	v_add_f32_e32 v216, v216, v78
	v_add_f32_e32 v216, v216, v80
	ds_read_b128 v[230:233], v235 offset:4672
	s_waitcnt lgkmcnt(1)
	v_mfma_f32_32x32x16_bf16 v[50:65], v[226:229], v[186:189], v[50:65]
	ds_read_b128 v[246:249], v235 offset:96
	v_mfma_f32_32x32x16_bf16 v[16:31], v[226:229], v[218:221], v[16:31]
	v_exp_f32_e32 v114, v114
	v_exp_f32_e32 v115, v115
	v_exp_f32_e32 v116, v116
	v_exp_f32_e32 v117, v117
	v_exp_f32_e32 v118, v118
	s_waitcnt lgkmcnt(1)
	v_mfma_f32_32x32x16_bf16 v[34:49], v[230:233], v[186:189], v[34:49]
	v_exp_f32_e32 v119, v119
	v_exp_f32_e32 v120, v120
	v_exp_f32_e32 v121, v121
	v_cvt_pk_bf16_f32 v170, v114, v115
	v_add_f32_e32 v114, v114, v115
	ds_read_b128 v[226:229], v235 offset:4704
	v_mfma_f32_32x32x16_bf16 v[0:15], v[230:233], v[218:221], v[0:15]
	v_exp_f32_e32 v122, v122
	v_exp_f32_e32 v123, v123
	v_cvt_pk_bf16_f32 v171, v116, v117
	v_add_f32_e32 v116, v116, v117
	v_add_f32_e32 v217, v217, v114
	v_exp_f32_e32 v124, v124
	v_add_u32_e32 v235, s41, v32
	s_waitcnt lgkmcnt(1)
	v_mfma_f32_32x32x16_bf16 v[50:65], v[246:249], v[190:193], v[50:65]
	v_exp_f32_e32 v125, v125
	v_cvt_pk_bf16_f32 v172, v118, v119
	v_add_f32_e32 v118, v118, v119
	v_add_f32_e32 v217, v217, v116
	v_exp_f32_e32 v126, v126
	ds_read_b128 v[230:233], v234 offset:4608
	v_mfma_f32_32x32x16_bf16 v[16:31], v[246:249], v[222:225], v[16:31]
	v_exp_f32_e32 v127, v127
	v_cvt_pk_bf16_f32 v173, v120, v121
	v_add_f32_e32 v120, v120, v121
	v_add_f32_e32 v217, v217, v118
	v_exp_f32_e32 v128, v128
	s_waitcnt lgkmcnt(1)
	v_mfma_f32_32x32x16_bf16 v[34:49], v[226:229], v[190:193], v[34:49]
	v_exp_f32_e32 v129, v129
	v_cvt_pk_bf16_f32 v166, v122, v123
	v_add_f32_e32 v122, v122, v123
	v_add_f32_e32 v217, v217, v120
	v_exp_f32_e32 v98, v98
	v_exp_f32_e32 v99, v99
	ds_read_b128 v[246:249], v234 offset:4640
	v_mfma_f32_32x32x16_bf16 v[0:15], v[226:229], v[222:225], v[0:15]
	v_cvt_pk_bf16_f32 v167, v124, v125
	v_add_f32_e32 v124, v124, v125
	v_add_f32_e32 v217, v217, v122
	v_exp_f32_e32 v100, v100
	v_exp_f32_e32 v101, v101
	s_waitcnt lgkmcnt(1)
	v_mfma_f32_32x32x16_bf16 v[82:97], v[230:233], v[130:133], 0
	v_cvt_pk_bf16_f32 v168, v126, v127
	v_add_f32_e32 v126, v126, v127
	v_add_f32_e32 v217, v217, v124
	v_exp_f32_e32 v102, v102
	v_exp_f32_e32 v103, v103
	ds_read_b128 v[226:229], v234 offset:4672
	v_mfma_f32_32x32x16_bf16 v[66:81], v[230:233], v[146:149], 0
	v_cvt_pk_bf16_f32 v169, v128, v129
	v_add_f32_e32 v128, v128, v129
	v_add_f32_e32 v217, v217, v126
	v_exp_f32_e32 v104, v104
	v_exp_f32_e32 v105, v105
	v_cvt_pk_bf16_f32 v174, v98, v99
	s_waitcnt lgkmcnt(1)
	v_mfma_f32_32x32x16_bf16 v[82:97], v[246:249], v[134:137], v[82:97]
	v_add_f32_e32 v98, v98, v99
	v_add_f32_e32 v217, v217, v128
	v_exp_f32_e32 v106, v106
	v_exp_f32_e32 v107, v107
	v_cvt_pk_bf16_f32 v175, v100, v101
	ds_read_b128 v[230:233], v234 offset:4704
	v_mfma_f32_32x32x16_bf16 v[66:81], v[246:249], v[150:153], v[66:81]
	v_add_f32_e32 v100, v100, v101
	v_add_f32_e32 v216, v216, v98
	v_exp_f32_e32 v108, v108
	v_exp_f32_e32 v109, v109
	v_cvt_pk_bf16_f32 v176, v102, v103
	v_add_u32_e32 v234, s43, v245
	s_waitcnt lgkmcnt(1)
	v_mfma_f32_32x32x16_bf16 v[82:97], v[226:229], v[138:141], v[82:97]
	v_add_f32_e32 v102, v102, v103
	v_add_f32_e32 v216, v216, v100
	v_exp_f32_e32 v110, v110
	v_exp_f32_e32 v111, v111
	v_cvt_pk_bf16_f32 v177, v104, v105
	v_add_f32_e32 v104, v104, v105
	v_mfma_f32_32x32x16_bf16 v[66:81], v[226:229], v[154:157], v[66:81]
	v_add_f32_e32 v216, v216, v102
	v_exp_f32_e32 v112, v112
	v_exp_f32_e32 v113, v113
	v_cvt_pk_bf16_f32 v162, v106, v107
	v_add_f32_e32 v106, v106, v107
	ds_read_b128 v[226:229], v235
	s_waitcnt lgkmcnt(1)
	v_mfma_f32_32x32x16_bf16 v[82:97], v[230:233], v[142:145], v[82:97]
	v_add_f32_e32 v216, v216, v104
	v_cvt_pk_bf16_f32 v163, v108, v109
	v_add_f32_e32 v108, v108, v109
	v_add_f32_e32 v216, v216, v106
	v_cvt_pk_bf16_f32 v164, v110, v111
	v_mfma_f32_32x32x16_bf16 v[66:81], v[230:233], v[158:161], v[66:81]
	v_add_f32_e32 v110, v110, v111
	v_add_f32_e32 v216, v216, v108
	v_cvt_pk_bf16_f32 v165, v112, v113
	v_add_f32_e32 v112, v112, v113
	v_add_f32_e32 v216, v216, v110
	v_add_f32_e32 v216, v216, v112
	ds_read_b128 v[230:233], v235 offset:4608
	s_mov_b32 s6, s5
	s_mov_b32 s5, s41
	s_mov_b32 s41, s42
	s_mov_b32 s42, s6
	s_mov_b32 s4, s44
	s_cmp_eq_u32 s44, 64
	s_barrier
	s_cbranch_scc0 .LBB0_1013
	s_waitcnt vmcnt(0)
	v_exp_f32_e32 v82, v82
	v_exp_f32_e32 v83, v83
	v_exp_f32_e32 v84, v84
	v_exp_f32_e32 v85, v85
	v_add_f32_e32 v98, 0, v82
	v_exp_f32_e32 v99, v86
	v_add_f32_e32 v98, v83, v98
	v_add_f32_e32 v98, v84, v98
	v_add_f32_e32 v98, v85, v98
	v_add_f32_e32 v86, v99, v98
	v_exp_f32_e32 v98, v87
	v_exp_f32_e32 v100, v88
	v_exp_f32_e32 v89, v89
	v_exp_f32_e32 v101, v90
	v_add_f32_e32 v86, v98, v86
	v_exp_f32_e32 v91, v91
	v_add_f32_e32 v86, v100, v86
	v_exp_f32_e32 v92, v92
	v_add_f32_e32 v86, v89, v86
	v_exp_f32_e32 v93, v93
	v_add_f32_e32 v86, v101, v86
	v_exp_f32_e32 v94, v94
	v_add_f32_e32 v86, v91, v86
	v_exp_f32_e32 v95, v95
	v_add_f32_e32 v86, v92, v86
	v_exp_f32_e32 v96, v96
	v_add_f32_e32 v86, v93, v86
	v_exp_f32_e32 v97, v97
	v_add_f32_e32 v86, v94, v86
	v_exp_f32_e32 v66, v66
	v_add_f32_e32 v86, v95, v86
	v_exp_f32_e32 v67, v67
	v_add_f32_e32 v86, v96, v86
	v_exp_f32_e32 v68, v68
	v_add_f32_e32 v86, v97, v86
	v_exp_f32_e32 v69, v69
	v_add_f32_e32 v90, v217, v86
	v_cvt_pk_bf16_f32 v86, v82, v83
	v_cvt_pk_bf16_f32 v82, v101, v91
	v_cvt_pk_bf16_f32 v83, v92, v93
	v_add_f32_e32 v91, 0, v66
	v_exp_f32_e32 v92, v70
	v_add_f32_e32 v91, v67, v91
	v_add_f32_e32 v91, v68, v91
	v_add_f32_e32 v91, v69, v91
	v_add_f32_e32 v70, v92, v91
	v_exp_f32_e32 v91, v71
	v_exp_f32_e32 v93, v72
	v_exp_f32_e32 v73, v73
	v_cvt_pk_bf16_f32 v87, v84, v85
	v_cvt_pk_bf16_f32 v84, v94, v95
	v_exp_f32_e32 v94, v74
	v_add_f32_e32 v70, v91, v70
	v_exp_f32_e32 v75, v75
	v_add_f32_e32 v70, v93, v70
	v_exp_f32_e32 v76, v76
	v_add_f32_e32 v70, v73, v70
	v_exp_f32_e32 v77, v77
	v_add_f32_e32 v70, v94, v70
	v_exp_f32_e32 v78, v78
	v_add_f32_e32 v70, v75, v70
	v_exp_f32_e32 v79, v79
	v_add_f32_e32 v70, v76, v70
	v_exp_f32_e32 v80, v80
	v_add_f32_e32 v70, v77, v70
	v_exp_f32_e32 v81, v81
	v_add_f32_e32 v70, v78, v70
	v_add_f32_e32 v70, v79, v70
	v_add_f32_e32 v70, v80, v70
	v_add_f32_e32 v70, v81, v70
	v_add_f32_e32 v74, v216, v70
	v_cvt_pk_bf16_f32 v70, v66, v67
	v_cvt_pk_bf16_f32 v71, v68, v69
	v_cvt_pk_bf16_f32 v72, v92, v91
	v_cvt_pk_bf16_f32 v73, v93, v73
	v_cvt_pk_bf16_f32 v66, v94, v75
	v_cvt_pk_bf16_f32 v67, v76, v77
	v_cvt_pk_bf16_f32 v68, v78, v79
	ds_read_b128 v[76:79], v32 offset:18432
	ds_read_b128 v[92:95], v32 offset:18464
	s_waitcnt lgkmcnt(1)
	v_mfma_f32_32x32x16_bf16 v[50:65], v[76:79], v[170:173], v[50:65]
	v_cvt_pk_bf16_f32 v88, v99, v98
	v_cvt_pk_bf16_f32 v89, v100, v89
	v_cvt_pk_bf16_f32 v85, v96, v97
	v_cvt_pk_bf16_f32 v69, v80, v81
	s_lshl_b32 s4, s39, 12
	s_add_i32 s40, s40, s4
	s_lshl_b32 s16, s1, 7
	v_mfma_f32_32x32x16_bf16 v[16:31], v[76:79], v[174:177], v[16:31]
	ds_read_b128 v[76:79], v32 offset:23040
	s_add_i32 s0, s0, s78
	s_cmpk_gt_i32 s0, 0x3ff
	s_waitcnt lgkmcnt(0)
	v_mfma_f32_32x32x16_bf16 v[34:49], v[76:79], v[170:173], v[34:49]
	v_mfma_f32_32x32x16_bf16 v[0:15], v[76:79], v[174:177], v[0:15]
	ds_read_b128 v[76:79], v32 offset:23072
	s_waitcnt lgkmcnt(0)
	v_mfma_f32_32x32x16_bf16 v[34:49], v[76:79], v[166:169], v[34:49]
	v_mfma_f32_32x32x16_bf16 v[0:15], v[76:79], v[162:165], v[0:15]
	ds_read_b128 v[76:79], v32 offset:18496
	v_mfma_f32_32x32x16_bf16 v[50:65], v[92:95], v[166:169], v[50:65]
	v_mfma_f32_32x32x16_bf16 v[16:31], v[92:95], v[162:165], v[16:31]
	s_waitcnt lgkmcnt(0)
	v_mfma_f32_32x32x16_bf16 v[50:65], v[76:79], v[86:89], v[50:65]
	v_mfma_f32_32x32x16_bf16 v[16:31], v[76:79], v[70:73], v[16:31]
	ds_read_b128 v[76:79], v32 offset:23104
	s_waitcnt lgkmcnt(0)
	v_mfma_f32_32x32x16_bf16 v[0:15], v[76:79], v[70:73], v[0:15]
	ds_read_b128 v[70:73], v32 offset:18528
	s_waitcnt lgkmcnt(0)
	v_mfma_f32_32x32x16_bf16 v[50:65], v[70:73], v[82:85], v[50:65]
	v_mfma_f32_32x32x16_bf16 v[16:31], v[70:73], v[66:69], v[16:31]
	ds_read_b128 v[70:73], v32 offset:23136
	s_waitcnt lgkmcnt(0)
	s_barrier
	v_mfma_f32_32x32x16_bf16 v[34:49], v[76:79], v[86:89], v[34:49]
	v_mfma_f32_32x32x16_bf16 v[0:15], v[70:73], v[66:69], v[0:15]
	ds_bpermute_b32 v69, v244, v90
	v_or_b32_e32 v68, s40, v202
	v_lshl_add_u64 v[66:67], v[206:207], 0, s[16:17]
	s_waitcnt lgkmcnt(0)
	v_add_f32_e32 v69, v90, v69
	v_mfma_f32_32x32x16_bf16 v[34:49], v[70:73], v[82:85], v[34:49]
	v_div_scale_f32 v70, s[4:5], v69, v69, 1.0
	v_rcp_f32_e32 v71, v70
	s_nop 0
	v_fma_f32 v72, -v70, v71, 1.0
	v_fmac_f32_e32 v71, v72, v71
	v_div_scale_f32 v72, vcc, 1.0, v69, 1.0
	v_mul_f32_e32 v73, v72, v71
	v_fma_f32 v75, -v70, v73, v72
	v_fmac_f32_e32 v73, v75, v71
	v_fma_f32 v70, -v70, v73, v72
	v_div_fmas_f32 v70, v70, v71, v73
	v_div_fixup_f32 v70, v70, v69, 1.0
	v_ashrrev_i32_e32 v69, 31, v68
	v_lshlrev_b64 v[72:73], 11, v[68:69]
	v_pk_mul_f32 v[34:35], v[34:35], v[70:71] op_sel_hi:[1,0]
	v_pk_mul_f32 v[36:37], v[36:37], v[70:71] op_sel_hi:[1,0]
	v_lshl_add_u64 v[72:73], v[66:67], 0, v[72:73]
	v_cvt_pk_bf16_f32 v34, v34, v35
	v_cvt_pk_bf16_f32 v35, v36, v37
	global_store_dwordx2 v[72:73], v[34:35], off offset:64
	v_pk_mul_f32 v[34:35], v[38:39], v[70:71] op_sel_hi:[1,0]
	v_pk_mul_f32 v[36:37], v[40:41], v[70:71] op_sel_hi:[1,0]
	v_cvt_pk_bf16_f32 v34, v34, v35
	v_cvt_pk_bf16_f32 v35, v36, v37
	global_store_dwordx2 v[72:73], v[34:35], off offset:80
	v_pk_mul_f32 v[34:35], v[42:43], v[70:71] op_sel_hi:[1,0]
	v_pk_mul_f32 v[36:37], v[44:45], v[70:71] op_sel_hi:[1,0]
	v_cvt_pk_bf16_f32 v34, v34, v35
	v_cvt_pk_bf16_f32 v35, v36, v37
	global_store_dwordx2 v[72:73], v[34:35], off offset:96
	v_pk_mul_f32 v[34:35], v[46:47], v[70:71] op_sel_hi:[1,0]
	v_pk_mul_f32 v[36:37], v[48:49], v[70:71] op_sel_hi:[1,0]
	v_cvt_pk_bf16_f32 v34, v34, v35
	v_cvt_pk_bf16_f32 v35, v36, v37
	global_store_dwordx2 v[72:73], v[34:35], off offset:112
	ds_bpermute_b32 v34, v244, v74
	v_pk_mul_f32 v[50:51], v[50:51], v[70:71] op_sel_hi:[1,0]
	v_pk_mul_f32 v[52:53], v[52:53], v[70:71] op_sel_hi:[1,0]
	v_cvt_pk_bf16_f32 v50, v50, v51
	v_cvt_pk_bf16_f32 v51, v52, v53
	s_waitcnt lgkmcnt(0)
	v_add_f32_e32 v34, v74, v34
	v_div_scale_f32 v35, s[4:5], v34, v34, 1.0
	v_rcp_f32_e32 v36, v35
	global_store_dwordx2 v[72:73], v[50:51], off
	v_pk_mul_f32 v[50:51], v[54:55], v[70:71] op_sel_hi:[1,0]
	v_pk_mul_f32 v[52:53], v[56:57], v[70:71] op_sel_hi:[1,0]
	v_fma_f32 v37, -v35, v36, 1.0
	v_fmac_f32_e32 v36, v37, v36
	v_div_scale_f32 v37, vcc, 1.0, v34, 1.0
	v_mul_f32_e32 v38, v37, v36
	v_fma_f32 v39, -v35, v38, v37
	v_fmac_f32_e32 v38, v39, v36
	v_fma_f32 v35, -v35, v38, v37
	v_div_fmas_f32 v35, v35, v36, v38
	v_or_b32_e32 v36, 32, v68
	v_div_fixup_f32 v34, v35, v34, 1.0
	v_ashrrev_i32_e32 v37, 31, v36
	v_lshlrev_b64 v[36:37], 11, v[36:37]
	v_pk_mul_f32 v[16:17], v[16:17], v[34:35] op_sel_hi:[1,0]
	v_pk_mul_f32 v[18:19], v[18:19], v[34:35] op_sel_hi:[1,0]
	v_pk_mul_f32 v[0:1], v[0:1], v[34:35] op_sel_hi:[1,0]
	v_pk_mul_f32 v[2:3], v[2:3], v[34:35] op_sel_hi:[1,0]
	v_lshl_add_u64 v[36:37], v[66:67], 0, v[36:37]
	v_cvt_pk_bf16_f32 v16, v16, v17
	v_cvt_pk_bf16_f32 v17, v18, v19
	v_cvt_pk_bf16_f32 v0, v0, v1
	v_cvt_pk_bf16_f32 v1, v2, v3
	global_store_dwordx2 v[36:37], v[16:17], off
	v_pk_mul_f32 v[16:17], v[20:21], v[34:35] op_sel_hi:[1,0]
	v_pk_mul_f32 v[18:19], v[22:23], v[34:35] op_sel_hi:[1,0]
	global_store_dwordx2 v[36:37], v[0:1], off offset:64
	v_pk_mul_f32 v[0:1], v[4:5], v[34:35] op_sel_hi:[1,0]
	v_pk_mul_f32 v[2:3], v[6:7], v[34:35] op_sel_hi:[1,0]
	v_cvt_pk_bf16_f32 v50, v50, v51
	v_cvt_pk_bf16_f32 v51, v52, v53
	v_cvt_pk_bf16_f32 v16, v16, v17
	v_cvt_pk_bf16_f32 v17, v18, v19
	v_cvt_pk_bf16_f32 v0, v0, v1
	v_cvt_pk_bf16_f32 v1, v2, v3
	global_store_dwordx2 v[72:73], v[50:51], off offset:16
	v_pk_mul_f32 v[50:51], v[58:59], v[70:71] op_sel_hi:[1,0]
	v_pk_mul_f32 v[52:53], v[60:61], v[70:71] op_sel_hi:[1,0]
	global_store_dwordx2 v[36:37], v[16:17], off offset:16
	v_pk_mul_f32 v[16:17], v[24:25], v[34:35] op_sel_hi:[1,0]
	v_pk_mul_f32 v[18:19], v[26:27], v[34:35] op_sel_hi:[1,0]
	global_store_dwordx2 v[36:37], v[0:1], off offset:80
	v_pk_mul_f32 v[0:1], v[8:9], v[34:35] op_sel_hi:[1,0]
	v_pk_mul_f32 v[2:3], v[10:11], v[34:35] op_sel_hi:[1,0]
	v_cvt_pk_bf16_f32 v50, v50, v51
	v_cvt_pk_bf16_f32 v51, v52, v53
	v_cvt_pk_bf16_f32 v16, v16, v17
	v_cvt_pk_bf16_f32 v17, v18, v19
	v_cvt_pk_bf16_f32 v0, v0, v1
	v_cvt_pk_bf16_f32 v1, v2, v3
	global_store_dwordx2 v[72:73], v[50:51], off offset:32
	v_pk_mul_f32 v[50:51], v[62:63], v[70:71] op_sel_hi:[1,0]
	v_pk_mul_f32 v[52:53], v[64:65], v[70:71] op_sel_hi:[1,0]
	global_store_dwordx2 v[36:37], v[16:17], off offset:32
	v_pk_mul_f32 v[16:17], v[28:29], v[34:35] op_sel_hi:[1,0]
	v_pk_mul_f32 v[18:19], v[30:31], v[34:35] op_sel_hi:[1,0]
	global_store_dwordx2 v[36:37], v[0:1], off offset:96
	v_pk_mul_f32 v[0:1], v[12:13], v[34:35] op_sel_hi:[1,0]
	v_pk_mul_f32 v[2:3], v[14:15], v[34:35] op_sel_hi:[1,0]
	v_cvt_pk_bf16_f32 v50, v50, v51
	v_cvt_pk_bf16_f32 v51, v52, v53
	v_cvt_pk_bf16_f32 v16, v16, v17
	v_cvt_pk_bf16_f32 v17, v18, v19
	v_cvt_pk_bf16_f32 v0, v0, v1
	v_cvt_pk_bf16_f32 v1, v2, v3
	global_store_dwordx2 v[72:73], v[50:51], off offset:48
	global_store_dwordx2 v[36:37], v[16:17], off offset:48
	global_store_dwordx2 v[36:37], v[0:1], off offset:112
	s_cbranch_scc0 .LBB0_1012
	v_mov_b32_e32 v246, 0x60
	v_mov_b64_e32 v[248:249], 0x300
	v_mov_b64_e32 v[250:251], 0x2ff

.LBB0_1200:
	v_lshl_add_u32 v147, s5, 10, v142
	ds_read_b32 v146, v147
	v_lshl_or_b32 v145, s6, 9, v143
	s_lshl_b32 s5, s7, 21
	v_add3_u32 v145, s5, v141, v145
	s_andn2_b64 vcc, exec, s[40:41]
	s_waitcnt lgkmcnt(0)
	v_pk_mul_f32 v[122:123], v[122:123], v[146:147] op_sel_hi:[1,0]
	v_pk_mul_f32 v[126:127], v[126:127], v[146:147] op_sel_hi:[1,0]
	v_pk_mul_f32 v[124:125], v[124:125], v[146:147] op_sel_hi:[1,0]
	v_max_f32_e32 v122, 0, v122
	v_pk_mul_f32 v[128:129], v[128:129], v[146:147] op_sel_hi:[1,0]
	v_mul_f32_e32 v148, v122, v122
	v_max_f32_e32 v122, 0, v127
	v_max_f32_e32 v123, 0, v123
	v_max_f32_e32 v124, 0, v124
	v_max_f32_e32 v126, 0, v126
	v_mul_f32_e32 v122, v122, v122
	v_mul_f32_e32 v127, v123, v123
	v_max_f32_e32 v123, 0, v128
	v_mul_f32_e32 v128, v124, v124
	v_max_f32_e32 v124, 0, v129
	v_max_f32_e32 v125, 0, v125
	v_pk_mul_f32 v[116:117], v[116:117], v[146:147] op_sel_hi:[1,0]
	v_pk_mul_f32 v[114:115], v[114:115], v[146:147] op_sel_hi:[1,0]
	v_mul_f32_e32 v126, v126, v126
	v_mul_f32_e32 v123, v123, v123
	v_mul_f32_e32 v124, v124, v124
	v_mul_f32_e32 v125, v125, v125
	v_cvt_pk_bf16_f32 v122, v126, v122
	v_pk_mul_f32 v[120:121], v[120:121], v[146:147] op_sel_hi:[1,0]
	v_pk_mul_f32 v[118:119], v[118:119], v[146:147] op_sel_hi:[1,0]
	v_max_f32_e32 v114, 0, v114
	v_max_f32_e32 v115, 0, v115
	v_max_f32_e32 v116, 0, v116
	v_cvt_pk_bf16_f32 v123, v123, v124
	v_cvt_pk_bf16_f32 v124, v148, v127
	v_cvt_pk_bf16_f32 v125, v128, v125
	global_store_dwordx4 v145, v[122:125], s[42:43] nt
	v_max_f32_e32 v118, 0, v118
	v_max_f32_e32 v117, 0, v117
	v_mul_f32_e32 v122, v114, v114
	v_max_f32_e32 v114, 0, v119
	v_mul_f32_e32 v119, v115, v115
	v_max_f32_e32 v115, 0, v120
	v_mul_f32_e32 v120, v116, v116
	v_max_f32_e32 v116, 0, v121
	v_mul_f32_e32 v118, v118, v118
	v_mul_f32_e32 v114, v114, v114
	v_mul_f32_e32 v115, v115, v115
	v_mul_f32_e32 v116, v116, v116
	v_mul_f32_e32 v117, v117, v117
	v_cvt_pk_bf16_f32 v114, v118, v114
	v_cvt_pk_bf16_f32 v115, v115, v116
	v_cvt_pk_bf16_f32 v116, v122, v119
	v_cvt_pk_bf16_f32 v117, v120, v117
	ds_read_b32 v118, v147 offset:64
	v_or_b32_e32 v119, 0x100, v145
	global_store_dwordx4 v119, v[114:117], s[42:43] nt
	s_mov_b64 s[40:41], -1
	s_waitcnt lgkmcnt(0)
	v_pk_mul_f32 v[106:107], v[106:107], v[118:119] op_sel_hi:[1,0]
	v_pk_mul_f32 v[110:111], v[110:111], v[118:119] op_sel_hi:[1,0]
	v_pk_mul_f32 v[108:109], v[108:109], v[118:119] op_sel_hi:[1,0]
	v_max_f32_e32 v106, 0, v106
	v_pk_mul_f32 v[112:113], v[112:113], v[118:119] op_sel_hi:[1,0]
	v_mul_f32_e32 v115, v106, v106
	v_max_f32_e32 v106, 0, v111
	v_max_f32_e32 v107, 0, v107
	v_max_f32_e32 v108, 0, v108
	v_max_f32_e32 v110, 0, v110
	v_mul_f32_e32 v106, v106, v106
	v_mul_f32_e32 v111, v107, v107
	v_max_f32_e32 v107, 0, v112
	v_mul_f32_e32 v112, v108, v108
	v_max_f32_e32 v108, 0, v113
	v_max_f32_e32 v109, 0, v109
	v_pk_mul_f32 v[100:101], v[100:101], v[118:119] op_sel_hi:[1,0]
	v_pk_mul_f32 v[98:99], v[98:99], v[118:119] op_sel_hi:[1,0]
	v_add_u32_e32 v114, 0x20000, v145
	v_mul_f32_e32 v110, v110, v110
	v_mul_f32_e32 v107, v107, v107
	v_mul_f32_e32 v108, v108, v108
	v_mul_f32_e32 v109, v109, v109
	v_cvt_pk_bf16_f32 v106, v110, v106
	v_pk_mul_f32 v[104:105], v[104:105], v[118:119] op_sel_hi:[1,0]
	v_pk_mul_f32 v[102:103], v[102:103], v[118:119] op_sel_hi:[1,0]
	v_max_f32_e32 v98, 0, v98
	v_max_f32_e32 v99, 0, v99
	v_max_f32_e32 v100, 0, v100
	v_cvt_pk_bf16_f32 v107, v107, v108
	v_cvt_pk_bf16_f32 v108, v115, v111
	v_cvt_pk_bf16_f32 v109, v112, v109
	global_store_dwordx4 v114, v[106:109], s[42:43] nt
	v_max_f32_e32 v102, 0, v102
	v_max_f32_e32 v101, 0, v101
	v_mul_f32_e32 v106, v98, v98
	v_max_f32_e32 v98, 0, v103
	v_mul_f32_e32 v103, v99, v99
	v_max_f32_e32 v99, 0, v104
	v_mul_f32_e32 v104, v100, v100
	v_max_f32_e32 v100, 0, v105
	v_mul_f32_e32 v102, v102, v102
	v_mul_f32_e32 v98, v98, v98
	v_mul_f32_e32 v99, v99, v99
	v_mul_f32_e32 v100, v100, v100
	v_mul_f32_e32 v101, v101, v101
	v_cvt_pk_bf16_f32 v98, v102, v98
	v_cvt_pk_bf16_f32 v99, v99, v100
	v_cvt_pk_bf16_f32 v100, v106, v103
	v_cvt_pk_bf16_f32 v101, v104, v101
	ds_read_b32 v102, v147 offset:128
	v_add_u32_e32 v103, 0x20100, v145
	global_store_dwordx4 v103, v[98:101], s[42:43] nt
	s_waitcnt lgkmcnt(0)
	v_pk_mul_f32 v[90:91], v[90:91], v[102:103] op_sel_hi:[1,0]
	v_pk_mul_f32 v[94:95], v[94:95], v[102:103] op_sel_hi:[1,0]
	v_pk_mul_f32 v[92:93], v[92:93], v[102:103] op_sel_hi:[1,0]
	v_max_f32_e32 v90, 0, v90
	v_pk_mul_f32 v[96:97], v[96:97], v[102:103] op_sel_hi:[1,0]
	v_mul_f32_e32 v99, v90, v90
	v_max_f32_e32 v90, 0, v95
	v_max_f32_e32 v91, 0, v91
	v_max_f32_e32 v92, 0, v92
	v_max_f32_e32 v94, 0, v94
	v_mul_f32_e32 v90, v90, v90
	v_mul_f32_e32 v95, v91, v91
	v_max_f32_e32 v91, 0, v96
	v_mul_f32_e32 v96, v92, v92
	v_max_f32_e32 v92, 0, v97
	v_max_f32_e32 v93, 0, v93
	v_pk_mul_f32 v[84:85], v[84:85], v[102:103] op_sel_hi:[1,0]
	v_pk_mul_f32 v[82:83], v[82:83], v[102:103] op_sel_hi:[1,0]
	v_add_u32_e32 v98, 0x40000, v145
	v_mul_f32_e32 v94, v94, v94
	v_mul_f32_e32 v91, v91, v91
	v_mul_f32_e32 v92, v92, v92
	v_mul_f32_e32 v93, v93, v93
	v_cvt_pk_bf16_f32 v90, v94, v90
	v_pk_mul_f32 v[88:89], v[88:89], v[102:103] op_sel_hi:[1,0]
	v_pk_mul_f32 v[86:87], v[86:87], v[102:103] op_sel_hi:[1,0]
	v_max_f32_e32 v82, 0, v82
	v_max_f32_e32 v83, 0, v83
	v_max_f32_e32 v84, 0, v84
	v_cvt_pk_bf16_f32 v91, v91, v92
	v_cvt_pk_bf16_f32 v92, v99, v95
	v_cvt_pk_bf16_f32 v93, v96, v93
	global_store_dwordx4 v98, v[90:93], s[42:43] nt
	v_max_f32_e32 v86, 0, v86
	v_max_f32_e32 v85, 0, v85
	v_mul_f32_e32 v90, v82, v82
	v_max_f32_e32 v82, 0, v87
	v_mul_f32_e32 v87, v83, v83
	v_max_f32_e32 v83, 0, v88
	v_mul_f32_e32 v88, v84, v84
	v_max_f32_e32 v84, 0, v89
	v_mul_f32_e32 v86, v86, v86
	v_mul_f32_e32 v82, v82, v82
	v_mul_f32_e32 v83, v83, v83
	v_mul_f32_e32 v84, v84, v84
	v_mul_f32_e32 v85, v85, v85
	v_cvt_pk_bf16_f32 v82, v86, v82
	v_cvt_pk_bf16_f32 v83, v83, v84
	v_cvt_pk_bf16_f32 v84, v90, v87
	v_cvt_pk_bf16_f32 v85, v88, v85
	ds_read_b32 v86, v147 offset:192
	v_add_u32_e32 v87, 0x40100, v145
	global_store_dwordx4 v87, v[82:85], s[42:43] nt
	s_waitcnt lgkmcnt(0)
	v_pk_mul_f32 v[74:75], v[74:75], v[86:87] op_sel_hi:[1,0]
	v_pk_mul_f32 v[78:79], v[78:79], v[86:87] op_sel_hi:[1,0]
	v_pk_mul_f32 v[76:77], v[76:77], v[86:87] op_sel_hi:[1,0]
	v_max_f32_e32 v74, 0, v74
	v_pk_mul_f32 v[80:81], v[80:81], v[86:87] op_sel_hi:[1,0]
	v_mul_f32_e32 v83, v74, v74
	v_max_f32_e32 v74, 0, v79
	v_max_f32_e32 v75, 0, v75
	v_max_f32_e32 v76, 0, v76
	v_max_f32_e32 v78, 0, v78
	v_mul_f32_e32 v74, v74, v74
	v_mul_f32_e32 v79, v75, v75
	v_max_f32_e32 v75, 0, v80
	v_mul_f32_e32 v80, v76, v76
	v_max_f32_e32 v76, 0, v81
	v_max_f32_e32 v77, 0, v77
	v_pk_mul_f32 v[68:69], v[68:69], v[86:87] op_sel_hi:[1,0]
	v_pk_mul_f32 v[66:67], v[66:67], v[86:87] op_sel_hi:[1,0]
	v_add_u32_e32 v82, 0x60000, v145
	v_mul_f32_e32 v78, v78, v78
	v_mul_f32_e32 v75, v75, v75
	v_mul_f32_e32 v76, v76, v76
	v_mul_f32_e32 v77, v77, v77
	v_cvt_pk_bf16_f32 v74, v78, v74
	v_pk_mul_f32 v[72:73], v[72:73], v[86:87] op_sel_hi:[1,0]
	v_pk_mul_f32 v[70:71], v[70:71], v[86:87] op_sel_hi:[1,0]
	v_max_f32_e32 v66, 0, v66
	v_max_f32_e32 v67, 0, v67
	v_max_f32_e32 v68, 0, v68
	v_cvt_pk_bf16_f32 v75, v75, v76
	v_cvt_pk_bf16_f32 v76, v83, v79
	v_cvt_pk_bf16_f32 v77, v80, v77
	global_store_dwordx4 v82, v[74:77], s[42:43] nt
	v_max_f32_e32 v70, 0, v70
	v_max_f32_e32 v69, 0, v69
	v_mul_f32_e32 v74, v66, v66
	v_max_f32_e32 v66, 0, v71
	v_mul_f32_e32 v71, v67, v67
	v_max_f32_e32 v67, 0, v72
	v_mul_f32_e32 v72, v68, v68
	v_max_f32_e32 v68, 0, v73
	v_mul_f32_e32 v70, v70, v70
	v_mul_f32_e32 v66, v66, v66
	v_mul_f32_e32 v67, v67, v67
	v_mul_f32_e32 v68, v68, v68
	v_mul_f32_e32 v69, v69, v69
	v_cvt_pk_bf16_f32 v66, v70, v66
	v_cvt_pk_bf16_f32 v67, v67, v68
	v_cvt_pk_bf16_f32 v68, v74, v71
	v_cvt_pk_bf16_f32 v69, v72, v69
	ds_read_b32 v70, v147 offset:512
	v_add_u32_e32 v71, 0x60100, v145
	global_store_dwordx4 v71, v[66:69], s[42:43] nt
	s_waitcnt lgkmcnt(0)
	v_pk_mul_f32 v[58:59], v[58:59], v[70:71] op_sel_hi:[1,0]
	v_pk_mul_f32 v[62:63], v[62:63], v[70:71] op_sel_hi:[1,0]
	v_pk_mul_f32 v[60:61], v[60:61], v[70:71] op_sel_hi:[1,0]
	v_max_f32_e32 v58, 0, v58
	v_pk_mul_f32 v[64:65], v[64:65], v[70:71] op_sel_hi:[1,0]
	v_mul_f32_e32 v67, v58, v58
	v_max_f32_e32 v58, 0, v63
	v_max_f32_e32 v59, 0, v59
	v_max_f32_e32 v60, 0, v60
	v_max_f32_e32 v62, 0, v62
	v_mul_f32_e32 v58, v58, v58
	v_mul_f32_e32 v63, v59, v59
	v_max_f32_e32 v59, 0, v64
	v_mul_f32_e32 v64, v60, v60
	v_max_f32_e32 v60, 0, v65
	v_max_f32_e32 v61, 0, v61
	v_pk_mul_f32 v[52:53], v[52:53], v[70:71] op_sel_hi:[1,0]
	v_pk_mul_f32 v[50:51], v[50:51], v[70:71] op_sel_hi:[1,0]
	v_add_u32_e32 v66, 0x100000, v145
	v_mul_f32_e32 v62, v62, v62
	v_mul_f32_e32 v59, v59, v59
	v_mul_f32_e32 v60, v60, v60
	v_mul_f32_e32 v61, v61, v61
	v_cvt_pk_bf16_f32 v58, v62, v58
	v_pk_mul_f32 v[56:57], v[56:57], v[70:71] op_sel_hi:[1,0]
	v_pk_mul_f32 v[54:55], v[54:55], v[70:71] op_sel_hi:[1,0]
	v_max_f32_e32 v50, 0, v50
	v_max_f32_e32 v51, 0, v51
	v_max_f32_e32 v52, 0, v52
	v_cvt_pk_bf16_f32 v59, v59, v60
	v_cvt_pk_bf16_f32 v60, v67, v63
	v_cvt_pk_bf16_f32 v61, v64, v61
	global_store_dwordx4 v66, v[58:61], s[42:43] nt
	v_max_f32_e32 v54, 0, v54
	v_max_f32_e32 v53, 0, v53
	v_mul_f32_e32 v58, v50, v50
	v_max_f32_e32 v50, 0, v55
	v_mul_f32_e32 v55, v51, v51
	v_max_f32_e32 v51, 0, v56
	v_mul_f32_e32 v56, v52, v52
	v_max_f32_e32 v52, 0, v57
	v_mul_f32_e32 v54, v54, v54
	v_mul_f32_e32 v50, v50, v50
	v_mul_f32_e32 v51, v51, v51
	v_mul_f32_e32 v52, v52, v52
	v_mul_f32_e32 v53, v53, v53
	v_cvt_pk_bf16_f32 v50, v54, v50
	v_cvt_pk_bf16_f32 v51, v51, v52
	v_cvt_pk_bf16_f32 v52, v58, v55
	v_cvt_pk_bf16_f32 v53, v56, v53
	ds_read_b32 v54, v147 offset:576
	v_add_u32_e32 v55, 0x100100, v145
	global_store_dwordx4 v55, v[50:53], s[42:43] nt
	s_waitcnt lgkmcnt(0)
	v_pk_mul_f32 v[42:43], v[42:43], v[54:55] op_sel_hi:[1,0]
	v_pk_mul_f32 v[46:47], v[46:47], v[54:55] op_sel_hi:[1,0]
	v_pk_mul_f32 v[44:45], v[44:45], v[54:55] op_sel_hi:[1,0]
	v_max_f32_e32 v42, 0, v42
	v_pk_mul_f32 v[48:49], v[48:49], v[54:55] op_sel_hi:[1,0]
	v_mul_f32_e32 v51, v42, v42
	v_max_f32_e32 v42, 0, v47
	v_max_f32_e32 v43, 0, v43
	v_max_f32_e32 v44, 0, v44
	v_max_f32_e32 v46, 0, v46
	v_mul_f32_e32 v42, v42, v42
	v_mul_f32_e32 v47, v43, v43
	v_max_f32_e32 v43, 0, v48
	v_mul_f32_e32 v48, v44, v44
	v_max_f32_e32 v44, 0, v49
	v_max_f32_e32 v45, 0, v45
	v_pk_mul_f32 v[36:37], v[36:37], v[54:55] op_sel_hi:[1,0]
	v_pk_mul_f32 v[34:35], v[34:35], v[54:55] op_sel_hi:[1,0]
	v_add_u32_e32 v50, 0x120000, v145
	v_mul_f32_e32 v46, v46, v46
	v_mul_f32_e32 v43, v43, v43
	v_mul_f32_e32 v44, v44, v44
	v_mul_f32_e32 v45, v45, v45
	v_cvt_pk_bf16_f32 v42, v46, v42
	v_pk_mul_f32 v[40:41], v[40:41], v[54:55] op_sel_hi:[1,0]
	v_pk_mul_f32 v[38:39], v[38:39], v[54:55] op_sel_hi:[1,0]
	v_max_f32_e32 v34, 0, v34
	v_max_f32_e32 v35, 0, v35
	v_max_f32_e32 v36, 0, v36
	v_cvt_pk_bf16_f32 v43, v43, v44
	v_cvt_pk_bf16_f32 v44, v51, v47
	v_cvt_pk_bf16_f32 v45, v48, v45
	global_store_dwordx4 v50, v[42:45], s[42:43] nt
	v_max_f32_e32 v38, 0, v38
	v_max_f32_e32 v37, 0, v37
	v_mul_f32_e32 v42, v34, v34
	v_max_f32_e32 v34, 0, v39
	v_mul_f32_e32 v39, v35, v35
	v_max_f32_e32 v35, 0, v40
	v_mul_f32_e32 v40, v36, v36
	v_max_f32_e32 v36, 0, v41
	v_mul_f32_e32 v38, v38, v38
	v_mul_f32_e32 v34, v34, v34
	v_mul_f32_e32 v35, v35, v35
	v_mul_f32_e32 v36, v36, v36
	v_mul_f32_e32 v37, v37, v37
	v_cvt_pk_bf16_f32 v34, v38, v34
	v_cvt_pk_bf16_f32 v35, v35, v36
	v_cvt_pk_bf16_f32 v36, v42, v39
	v_cvt_pk_bf16_f32 v37, v40, v37
	ds_read_b32 v38, v147 offset:640
	v_add_u32_e32 v39, 0x120100, v145
	global_store_dwordx4 v39, v[34:37], s[42:43] nt
	s_waitcnt lgkmcnt(0)
	v_pk_mul_f32 v[24:25], v[24:25], v[38:39] op_sel_hi:[1,0]
	v_pk_mul_f32 v[28:29], v[28:29], v[38:39] op_sel_hi:[1,0]
	v_pk_mul_f32 v[26:27], v[26:27], v[38:39] op_sel_hi:[1,0]
	v_max_f32_e32 v24, 0, v24
	v_pk_mul_f32 v[30:31], v[30:31], v[38:39] op_sel_hi:[1,0]
	v_mul_f32_e32 v35, v24, v24
	v_max_f32_e32 v24, 0, v29
	v_max_f32_e32 v25, 0, v25
	v_max_f32_e32 v26, 0, v26
	v_max_f32_e32 v28, 0, v28
	v_mul_f32_e32 v24, v24, v24
	v_mul_f32_e32 v29, v25, v25
	v_max_f32_e32 v25, 0, v30
	v_mul_f32_e32 v30, v26, v26
	v_max_f32_e32 v26, 0, v31
	v_max_f32_e32 v27, 0, v27
	v_pk_mul_f32 v[18:19], v[18:19], v[38:39] op_sel_hi:[1,0]
	v_pk_mul_f32 v[16:17], v[16:17], v[38:39] op_sel_hi:[1,0]
	v_add_u32_e32 v34, 0x140000, v145
	v_mul_f32_e32 v28, v28, v28
	v_mul_f32_e32 v25, v25, v25
	v_mul_f32_e32 v26, v26, v26
	v_mul_f32_e32 v27, v27, v27
	v_cvt_pk_bf16_f32 v24, v28, v24
	v_pk_mul_f32 v[22:23], v[22:23], v[38:39] op_sel_hi:[1,0]
	v_pk_mul_f32 v[20:21], v[20:21], v[38:39] op_sel_hi:[1,0]
	v_max_f32_e32 v16, 0, v16
	v_max_f32_e32 v17, 0, v17
	v_max_f32_e32 v18, 0, v18
	v_cvt_pk_bf16_f32 v25, v25, v26
	v_cvt_pk_bf16_f32 v26, v35, v29
	v_cvt_pk_bf16_f32 v27, v30, v27
	global_store_dwordx4 v34, v[24:27], s[42:43] nt
	v_max_f32_e32 v20, 0, v20
	v_max_f32_e32 v19, 0, v19
	v_mul_f32_e32 v24, v16, v16
	v_max_f32_e32 v16, 0, v21
	v_mul_f32_e32 v21, v17, v17
	v_max_f32_e32 v17, 0, v22
	v_mul_f32_e32 v22, v18, v18
	v_max_f32_e32 v18, 0, v23
	v_mul_f32_e32 v20, v20, v20
	v_mul_f32_e32 v16, v16, v16
	v_mul_f32_e32 v17, v17, v17
	v_mul_f32_e32 v18, v18, v18
	v_mul_f32_e32 v19, v19, v19
	v_cvt_pk_bf16_f32 v16, v20, v16
	v_cvt_pk_bf16_f32 v17, v17, v18
	v_cvt_pk_bf16_f32 v18, v24, v21
	v_cvt_pk_bf16_f32 v19, v22, v19
	ds_read_b32 v20, v147 offset:704
	v_add_u32_e32 v21, 0x140100, v145
	global_store_dwordx4 v21, v[16:19], s[42:43] nt
	s_waitcnt lgkmcnt(0)
	v_pk_mul_f32 v[8:9], v[8:9], v[20:21] op_sel_hi:[1,0]
	v_pk_mul_f32 v[12:13], v[12:13], v[20:21] op_sel_hi:[1,0]
	v_pk_mul_f32 v[10:11], v[10:11], v[20:21] op_sel_hi:[1,0]
	v_max_f32_e32 v8, 0, v8
	v_pk_mul_f32 v[14:15], v[14:15], v[20:21] op_sel_hi:[1,0]
	v_mul_f32_e32 v17, v8, v8
	v_max_f32_e32 v8, 0, v13
	v_max_f32_e32 v9, 0, v9
	v_max_f32_e32 v10, 0, v10
	v_max_f32_e32 v12, 0, v12
	v_mul_f32_e32 v8, v8, v8
	v_mul_f32_e32 v13, v9, v9
	v_max_f32_e32 v9, 0, v14
	v_mul_f32_e32 v14, v10, v10
	v_max_f32_e32 v10, 0, v15
	v_max_f32_e32 v11, 0, v11
	v_pk_mul_f32 v[0:1], v[0:1], v[20:21] op_sel_hi:[1,0]
	v_add_u32_e32 v16, 0x160000, v145
	v_mul_f32_e32 v12, v12, v12
	v_mul_f32_e32 v9, v9, v9
	v_mul_f32_e32 v10, v10, v10
	v_mul_f32_e32 v11, v11, v11
	v_cvt_pk_bf16_f32 v8, v12, v8
	v_pk_mul_f32 v[4:5], v[4:5], v[20:21] op_sel_hi:[1,0]
	v_pk_mul_f32 v[2:3], v[2:3], v[20:21] op_sel_hi:[1,0]
	v_max_f32_e32 v0, 0, v0
	v_cvt_pk_bf16_f32 v9, v9, v10
	v_cvt_pk_bf16_f32 v10, v17, v13
	v_cvt_pk_bf16_f32 v11, v14, v11
	global_store_dwordx4 v16, v[8:11], s[42:43] nt
	v_pk_mul_f32 v[6:7], v[6:7], v[20:21] op_sel_hi:[1,0]
	v_max_f32_e32 v4, 0, v4
	v_mul_f32_e32 v8, v0, v0
	v_max_f32_e32 v0, 0, v5
	v_max_f32_e32 v1, 0, v1
	v_max_f32_e32 v2, 0, v2
	v_mul_f32_e32 v4, v4, v4
	v_mul_f32_e32 v0, v0, v0
	v_mul_f32_e32 v5, v1, v1
	v_max_f32_e32 v1, 0, v6
	v_mul_f32_e32 v6, v2, v2
	v_max_f32_e32 v2, 0, v7
	v_max_f32_e32 v3, 0, v3
	v_mul_f32_e32 v1, v1, v1
	v_mul_f32_e32 v2, v2, v2
	v_mul_f32_e32 v3, v3, v3
	v_cvt_pk_bf16_f32 v0, v4, v0
	v_add_u32_e32 v4, 0x160100, v145
	v_cvt_pk_bf16_f32 v1, v1, v2
	v_cvt_pk_bf16_f32 v2, v8, v5
	v_cvt_pk_bf16_f32 v3, v6, v3
	global_store_dwordx4 v4, v[0:3], s[42:43] nt
	s_cbranch_vccnz .LBB0_1189
	s_andn2_b64 vcc, exec, s[0:1]
	s_cbranch_vccnz .LBB0_1188
	s_barrier
	s_branch .LBB0_1188
